# P3 sample mini-GEMM overlapped with the main prologue's first LDS-DMA loads (renamed registers)
# speedup vs baseline: 1.0521x; 1.0019x over previous
.LBB0_485:
	s_ashr_i32 s0, s4, 3
	s_add_i32 s0, s3, s0
	s_ashr_i32 s3, s0, 31
	s_lshr_b32 s3, s3, 27
	s_add_i32 s3, s0, s3
	s_ashr_i32 s5, s3, 5
	s_andn2_b32 s3, s3, 31
	s_sub_i32 s3, s0, s3
	s_bfe_i32 s0, s3, 0x80000
	s_bfe_u32 s0, s0, 0x3000c
	s_add_i32 s14, s3, s0
	s_bfe_i32 s0, s14, 0x80000
	s_and_b32 s14, s14, 0xf8
	s_sub_i32 s3, s3, s14
	v_lshlrev_b32_e32 v0, 4, v201
	s_lshl_b32 s5, s5, 3
	s_sext_i32_i16 s0, s0
	s_sext_i32_i8 s3, s3
	s_lshr_b32 s1, s33, 6
	s_waitcnt lgkmcnt(0)
	v_and_b32_e32 v1, 32, v201
	s_waitcnt vmcnt(0)
	v_bfe_u32 v10, v201, 2, 4
	v_lshrrev_b32_e32 v2, 3, v201
	s_movk_i32 s4, 0x70
	v_add_u32_e32 v11, 0x2000, v0
	s_lshr_b32 s0, s0, 3
	s_add_i32 s14, s5, s3
	v_bitop3_b32 v8, v0, v1, 48 bitop3:0x6c
	v_and_or_b32 v2, v2, s4, v10
	v_lshrrev_b32_e32 v0, 7, v11
	s_movk_i32 s4, 0xf0
	s_ashr_i32 s15, s14, 31
	s_bfe_i64 s[18:19], s[0:1], 0x100000
	v_and_or_b32 v0, v0, s4, v10
	s_lshr_b32 s4, s33, 8
	s_lshl_b32 s39, s1, 10
	s_lshl_b64 s[16:17], s[14:15], 20
	s_lshl_b64 s[18:19], s[18:19], 20
	v_and_b32_e32 v9, 64, v201
	s_add_u32 s30, s88, s18
	v_or_b32_e32 v1, v8, v9
	s_addc_u32 s31, s89, s19
	s_add_i32 s40, s39, 0
	v_lshl_or_b32 v128, v2, 12, v1
	s_add_i32 m0, s40, 0x10000
	v_lshl_or_b32 v130, v0, 12, v1
	global_load_lds_dwordx4 v128, s[30:31]
	s_add_i32 m0, s40, 0x12000
	s_add_u32 s18, s30, 0x80000
	global_load_lds_dwordx4 v130, s[30:31]
	s_addc_u32 s19, s31, 0
	s_add_i32 m0, s40, 0x14000
	v_mov_b32_e32 v129, 0
	global_load_lds_dwordx4 v128, s[18:19]
	s_add_i32 m0, s40, 0x16000
	s_add_u32 s16, s12, s16
	s_addc_u32 s17, s13, s17
	s_add_i32 s41, s40, 0x2000
	global_load_lds_dwordx4 v130, s[18:19]
	s_mov_b32 m0, s40
	s_add_u32 s18, s16, 0x80000
	global_load_lds_dwordx4 v128, s[16:17]
	s_mov_b32 m0, s41
	s_addc_u32 s19, s17, 0
	s_add_i32 s43, s40, 0x4000
	global_load_lds_dwordx4 v130, s[16:17]
	s_mov_b32 m0, s43
	s_add_i32 s48, s40, 0x6000
	global_load_lds_dwordx4 v128, s[18:19]
	s_mov_b32 m0, s48
	v_mov_b32_e32 v131, v129
	global_load_lds_dwordx4 v130, s[18:19]
	v_lshl_add_u64 v[6:7], s[30:31], 0, v[128:129]
	v_lshl_add_u64 v[4:5], s[30:31], 0, v[130:131]
	v_lshl_add_u64 v[2:3], s[16:17], 0, v[128:129]
	s_lshl_b32 s62, s2, 1
	s_lshr_b32 s63, s79, 8
	s_add_i32 s32, s63, s62
	s_and_b32 s72, s32, 7
	v_lshl_or_b32 v144, s72, 4, v233
	s_bfe_u32 s73, s79, 0x20006
	v_lshlrev_b32_e32 v140, 12, v144
	v_mov_b32_e32 v141, 0
	s_mov_b32 s63, 0
	s_waitcnt lgkmcnt(0)
	v_lshl_add_u64 v[132:133], s[12:13], 0, v[140:141]
	s_lshl_b32 s62, s73, 10
	s_lshl_b32 s32, s32, 1
	v_lshl_add_u64 v[132:133], v[132:133], 0, s[62:63]
	v_lshlrev_b32_e32 v134, 4, v232
	v_mov_b32_e32 v135, v141
	s_and_b32 s32, s32, -16
	v_lshl_add_u64 v[142:143], v[132:133], 0, v[134:135]
	v_or_b32_e32 v132, s32, v233
	v_ashrrev_i32_e32 v133, 31, v132
	v_lshlrev_b64 v[132:133], 12, v[132:133]
	v_lshl_add_u64 v[132:133], s[88:89], 0, v[132:133]
	v_lshl_add_u64 v[132:133], v[132:133], 0, s[62:63]
	v_lshl_add_u64 v[210:211], v[132:133], 0, v[134:135]
	global_load_dwordx4 v[132:135], v[210:211], off
	s_brev_b32 s62, 32
	v_add_co_u32_e32 v150, vcc, s62, v142
	s_mov_b64 s[62:63], 0x4000000
	s_nop 0
	v_addc_co_u32_e32 v151, vcc, 0, v143, vcc
	global_load_dwordx4 v[136:139], v[150:151], off
	global_load_dwordx4 v[146:149], v[210:211], off offset:64
	v_lshl_add_u64 v[142:143], v[142:143], 0, s[62:63]
	global_load_dwordx4 v[150:153], v[210:211], off offset:128
	global_load_dwordx4 v[154:157], v[142:143], off offset:64
	global_load_dwordx4 v[158:161], v[142:143], off offset:128
	global_load_dwordx4 v[162:165], v[210:211], off offset:192
	global_load_dwordx4 v[166:169], v[210:211], off offset:256
	global_load_dwordx4 v[170:173], v[142:143], off offset:192
	global_load_dwordx4 v[174:177], v[142:143], off offset:256
	global_load_dwordx4 v[178:181], v[210:211], off offset:320
	global_load_dwordx4 v[182:185], v[142:143], off offset:320
	global_load_dwordx4 v[186:189], v[142:143], off offset:384
	global_load_dwordx4 v[190:193], v[210:211], off offset:384
	global_load_dwordx4 v[194:197], v[142:143], off offset:960
	global_load_dwordx4 v[202:205], v[210:211], off offset:960
	s_and_b32 s62, s79, 0xfffffc0
	s_lshl_b32 s62, s62, 4
	s_add_i32 s62, s62, 0x20800
	s_cmp_lg_u32 s73, 0
	s_waitcnt vmcnt(11)
	v_mfma_f32_16x16x32_bf16 v[146:149], v[146:149], v[154:157], 0
	v_mfma_f32_16x16x32_bf16 v[132:135], v[132:135], v[136:139], 0
	global_load_dwordx4 v[136:139], v[210:211], off offset:448
	global_load_dwordx4 v[206:209], v[142:143], off offset:448
	global_load_dwordx4 v[154:157], v[210:211], off offset:512
	s_waitcnt vmcnt(13)
	v_mfma_f32_16x16x32_bf16 v[132:135], v[150:153], v[158:161], v[132:135]
	global_load_dwordx4 v[150:153], v[142:143], off offset:512
	s_waitcnt vmcnt(11)
	v_mfma_f32_16x16x32_bf16 v[146:149], v[162:165], v[170:173], v[146:149]
	global_load_dwordx4 v[158:161], v[210:211], off offset:576
	global_load_dwordx4 v[162:165], v[210:211], off offset:640
	s_waitcnt vmcnt(12)
	v_mfma_f32_16x16x32_bf16 v[132:135], v[166:169], v[174:177], v[132:135]
	global_load_dwordx4 v[166:169], v[142:143], off offset:576
	global_load_dwordx4 v[170:173], v[142:143], off offset:640
	s_waitcnt vmcnt(12)
	v_mfma_f32_16x16x32_bf16 v[146:149], v[178:181], v[182:185], v[146:149]
	global_load_dwordx4 v[174:177], v[210:211], off offset:704
	global_load_dwordx4 v[178:181], v[210:211], off offset:768
	s_waitcnt vmcnt(12)
	v_mfma_f32_16x16x32_bf16 v[132:135], v[190:193], v[186:189], v[132:135]
	global_load_dwordx4 v[182:185], v[142:143], off offset:704
	global_load_dwordx4 v[186:189], v[142:143], off offset:768
	s_waitcnt vmcnt(10)
	v_mfma_f32_16x16x32_bf16 v[136:139], v[136:139], v[206:209], v[146:149]
	s_nop 2
	global_load_dwordx4 v[146:149], v[210:211], off offset:832
	s_waitcnt vmcnt(9)
	v_mfma_f32_16x16x32_bf16 v[132:135], v[154:157], v[150:153], v[132:135]
	global_load_dwordx4 v[150:153], v[142:143], off offset:832
	global_load_dwordx4 v[154:157], v[210:211], off offset:896
	s_waitcnt vmcnt(8)
	v_mfma_f32_16x16x32_bf16 v[136:139], v[158:161], v[166:169], v[136:139]
	global_load_dwordx4 v[158:161], v[142:143], off offset:896
	v_lshl_or_b32 v142, v232, 2, s32
	v_ashrrev_i32_e32 v143, 31, v142
	s_waitcnt vmcnt(8)
	v_mfma_f32_16x16x32_bf16 v[132:135], v[162:165], v[170:173], v[132:135]
	s_waitcnt vmcnt(5)
	v_mfma_f32_16x16x32_bf16 v[162:165], v[174:177], v[182:185], v[136:139]
	s_nop 2
	v_lshl_add_u64 v[136:137], s[46:47], 0, v[140:141]
	v_lshlrev_b64 v[138:139], 2, v[142:143]
	s_waitcnt vmcnt(4)
	v_mfma_f32_16x16x32_bf16 v[166:169], v[178:181], v[186:189], v[132:135]
	v_lshl_add_u32 v141, v200, 4, s62
	s_nop 1
	v_lshl_add_u64 v[132:133], v[136:137], 0, v[138:139]
	v_lshl_add_u64 v[134:135], s[64:65], 0, v[138:139]
	global_load_dwordx4 v[136:139], v[132:133], off
	s_waitcnt vmcnt(3)
	v_mfma_f32_16x16x32_bf16 v[146:149], v[146:149], v[150:153], v[162:165]
	global_load_dwordx4 v[132:135], v[134:135], off
	s_waitcnt vmcnt(2)
	v_mfma_f32_16x16x32_bf16 v[150:153], v[154:157], v[158:161], v[166:169]
	v_mfma_f32_16x16x32_bf16 v[146:149], v[202:205], v[194:197], v[146:149]
	s_nop 7
	v_pk_add_f32 v[148:149], v[152:153], v[148:149]
	v_pk_add_f32 v[146:147], v[150:151], v[146:147]
	ds_write_b128 v141, v[146:149]
	s_waitcnt lgkmcnt(0)
	s_barrier
	s_waitcnt vmcnt(0)
	s_cbranch_scc1 .Ls1_done
	s_and_b32 s62, s79, 0xfffff80
	ds_read_b128 v[146:149], v141
	s_lshl_b32 s62, s62, 4
	s_add_i32 s62, s62, 0x20800
	v_lshlrev_b32_e32 v141, 4, v200
	v_add_u32_e32 v145, s62, v141
	s_and_b32 s62, s79, 0xfffff40
	s_lshl_b32 s62, s62, 4
	s_add_i32 s62, s62, 0x20800
	s_waitcnt vmcnt(1) lgkmcnt(0)
	v_pk_add_f32 v[156:157], v[136:137], v[146:147]
	v_add_u32_e32 v136, s62, v141
	s_and_b32 s62, s79, 0xfffff00
	s_lshl_b32 s62, s62, 4
	ds_read_b128 v[150:153], v145 offset:1024
	s_add_i32 s62, s62, 0x20800
	v_pk_add_f32 v[154:155], v[138:139], v[148:149]
	ds_read_b128 v[136:139], v136 offset:2048
	v_add_u32_e32 v141, s62, v141
	ds_read_b128 v[146:149], v141 offset:3072
	s_waitcnt lgkmcnt(2)
	v_pk_add_f32 v[152:153], v[154:155], v[152:153]
	v_pk_add_f32 v[150:151], v[156:157], v[150:151]
	s_waitcnt lgkmcnt(1)
	v_pk_add_f32 v[138:139], v[152:153], v[138:139]
	v_pk_add_f32 v[150:151], v[150:151], v[136:137]
	s_waitcnt lgkmcnt(0)
	v_pk_add_f32 v[136:137], v[138:139], v[148:149]
	v_pk_add_f32 v[138:139], v[150:151], v[146:147]
	v_mul_f32_e32 v145, v137, v137
	v_mul_f32_e32 v141, v139, v139
	v_fmac_f32_e32 v141, v138, v138
	v_fmac_f32_e32 v145, v136, v136
	v_add_f32_e32 v141, v141, v145
	v_mbcnt_lo_u32_b32 v145, -1, 0
	v_mbcnt_hi_u32_b32 v145, -1, v145
	v_and_b32_e32 v147, 64, v145
	v_xor_b32_e32 v146, 16, v145
	v_add_u32_e32 v147, 64, v147
	v_cmp_lt_i32_e32 vcc, v146, v147
	v_lshlrev_b32_e32 v144, 2, v144
	s_nop 0
	v_cndmask_b32_e32 v146, v145, v146, vcc
	v_lshlrev_b32_e32 v146, 2, v146
	ds_bpermute_b32 v146, v146, v141
	s_waitcnt lgkmcnt(0)
	v_add_f32_e32 v141, v141, v146
	v_xor_b32_e32 v146, 32, v145
	v_cmp_lt_i32_e32 vcc, v146, v147
	s_nop 1
	v_cndmask_b32_e32 v145, v145, v146, vcc
	v_lshlrev_b32_e32 v145, 2, v145
	ds_bpermute_b32 v146, v145, v141
	s_waitcnt vmcnt(0)
	v_mov_b32_e32 v242, v132
	v_mov_b32_e32 v243, v133
	v_mov_b32_e32 v244, v134
	v_mov_b32_e32 v245, v135
	v_mov_b32_e32 v246, v136
	v_mov_b32_e32 v247, v137
	v_mov_b32_e32 v248, v138
	v_mov_b32_e32 v249, v139
	v_mov_b32_e32 v250, v140
	v_mov_b32_e32 v251, v142
	v_mov_b32_e32 v252, v144
	v_cmp_gt_u32_e32 vcc, 16, v200
	s_and_saveexec_b64 s[62:63], vcc
	s_cbranch_execz .Ls1_544
	v_mov_b32_e32 v145, 0
	v_lshl_add_u64 v[148:149], s[68:69], 0, v[144:145]
	s_waitcnt lgkmcnt(0)
	v_add_f32_e32 v141, v141, v146
	v_add_co_u32_e32 v146, vcc, 0x20000, v148
	s_nop 1
	v_addc_co_u32_e32 v147, vcc, 0, v149, vcc
	global_atomic_add_f32 v[146:147], v141, off offset:1024
.Ls1_544:
	s_or_b64 exec, exec, s[62:63]
.Ls1_done:
	s_cmp_lg_u32 s4, 1
	v_lshl_add_u64 v[0:1], s[16:17], 0, v[130:131]
	s_cbranch_scc1 .LBB0_487
	s_barrier
